# norm phases: wave index permuted so that the context rows carrying split-K partial sums are spread over all workgroups
# speedup vs baseline: 1.0224x; 1.0013x over previous
.LBB0_618:
	v_lshrrev_b32_e32 v210, 1, v176
	v_writelane_b32 v255, s83, 10
	v_writelane_b32 v255, s82, 11
	v_writelane_b32 v255, s85, 12
	v_writelane_b32 v255, s84, 13
	v_readfirstlane_b32 s8, v32
	v_readfirstlane_b32 s9, v33
	v_readfirstlane_b32 s10, v34
	v_readfirstlane_b32 s11, v35
	s_cmp_lg_u64 s[6:7], 0
	s_cselect_b32 s12, 1, 0
	s_mov_b32 s13, 0
	v_writelane_b32 v255, s8, 14
	v_writelane_b32 v255, s9, 15
	v_writelane_b32 v255, s10, 16
	v_writelane_b32 v255, s11, 17
	v_writelane_b32 v255, s12, 18
	v_writelane_b32 v255, s13, 19
	v_readfirstlane_b32 s10, v38
	v_readfirstlane_b32 s11, v39
	s_add_u32 s10, s10, 0x1000
	s_addc_u32 s11, s11, 0
	global_load_dwordx4 v[178:181], v176, s[10:11] offset:-4096
	global_load_dwordx4 v[182:185], v176, s[10:11] offset:-3072
	global_load_dwordx4 v[186:189], v176, s[10:11] offset:-2048
	global_load_dwordx4 v[190:193], v176, s[10:11] offset:-1024
	global_load_dwordx4 v[194:197], v176, s[10:11] offset:0
	global_load_dwordx4 v[198:201], v176, s[10:11] offset:1024
	global_load_dwordx4 v[202:205], v176, s[10:11] offset:2048
	global_load_dwordx4 v[206:209], v176, s[10:11] offset:3072
	s_and_b32 s3, s2, 7
	s_lshr_b32 s4, s88, 3
	s_mul_i32 s3, s3, s4
	s_lshr_b32 s4, s2, 3
	s_add_i32 s2, s3, s4
	s_sub_i32 s3, s2, s88

.Lfz_zskip:
	v_lshrrev_b32_e32 v210, 1, v176
	v_readlane_b32 s8, v254, 57
	v_readlane_b32 s9, v254, 58
	v_readlane_b32 s10, v253, 11
	v_readlane_b32 s11, v253, 12
	s_cmp_lg_u64 s[8:9], 0
	s_cselect_b32 s12, 1, 0
	s_cselect_b32 s10, s10, 0
	s_cselect_b32 s11, s11, 0
	s_mov_b32 s13, 0
	v_writelane_b32 v255, s13, 10
	v_writelane_b32 v255, s13, 11
	v_writelane_b32 v255, s10, 12
	v_writelane_b32 v255, s11, 13
	s_cmp_lg_u64 s[78:79], 0
	s_cselect_b32 s13, 1, 0
	v_readfirstlane_b32 s8, v32
	v_readfirstlane_b32 s9, v33
	v_readfirstlane_b32 s10, v36
	v_readfirstlane_b32 s11, v37
	v_writelane_b32 v255, s8, 14
	v_writelane_b32 v255, s9, 15
	v_writelane_b32 v255, s10, 16
	v_writelane_b32 v255, s11, 17
	v_writelane_b32 v255, s12, 18
	v_writelane_b32 v255, s13, 19
	v_readfirstlane_b32 s10, v38
	v_readfirstlane_b32 s11, v39
	s_add_u32 s10, s10, 0x1000
	s_addc_u32 s11, s11, 0
	global_load_dwordx4 v[178:181], v176, s[10:11] offset:-4096
	global_load_dwordx4 v[182:185], v176, s[10:11] offset:-3072
	global_load_dwordx4 v[186:189], v176, s[10:11] offset:-2048
	global_load_dwordx4 v[190:193], v176, s[10:11] offset:-1024
	global_load_dwordx4 v[194:197], v176, s[10:11] offset:0
	global_load_dwordx4 v[198:201], v176, s[10:11] offset:1024
	global_load_dwordx4 v[202:205], v176, s[10:11] offset:2048
	global_load_dwordx4 v[206:209], v176, s[10:11] offset:3072
	s_and_b32 s3, s2, 7
	s_lshr_b32 s4, s88, 3
	s_mul_i32 s3, s3, s4
	s_lshr_b32 s4, s2, 3
	s_add_i32 s2, s3, s4
	s_sub_i32 s3, s2, s88
